# mod_unit K loop double-buffered (32 w_ada loads in flight, pipelined across batches)
# speedup vs baseline: 1.0412x; 1.0016x over previous
.LBB0_671:
	s_or_b64 exec, exec, s[6:7]
	s_mul_hi_i32 s6, s12, 0x2aaaaaab
	s_lshr_b32 s7, s6, 31
	s_ashr_i32 s6, s6, 4
	s_add_i32 s6, s6, s7
	s_waitcnt lgkmcnt(0)
	s_barrier
	s_load_dwordx2 s[10:11], s[4:5], 0x38
	s_mul_i32 s7, s6, 0x60
	s_sub_i32 s7, s12, s7
	v_ashrrev_i32_e32 v42, 6, v37
	s_lshl_b32 s8, s7, 6
	s_ashr_i32 s7, s6, 31
	v_lshlrev_b32_e32 v0, 8, v42
	s_lshl_b64 s[14:15], s[6:7], 10
	v_ashrrev_i32_e32 v1, 31, v0
	v_lshl_add_u64 v[0:1], s[14:15], 0, v[0:1]
	s_waitcnt lgkmcnt(0)
	v_mov_b64_e32 v[2:3], s[10:11]
	v_mad_u64_u32 v[2:3], s[10:11], v0, s35, v[2:3]
	v_and_b32_e32 v36, 63, v37
	v_mad_i32_i24 v3, v1, s35, v3
	s_ashr_i32 s9, s8, 31
	v_lshl_add_u64 v[0:1], s[8:9], 2, v[2:3]
	v_lshlrev_b32_e32 v148, 2, v36
	v_mov_b32_e32 v8, 0
	v_lshl_add_u64 v[38:39], v[0:1], 0, v[148:149]
	v_lshlrev_b32_e32 v43, 10, v42
	s_mov_b64 s[10:11], 0
	v_mov_b32_e32 v9, v8
	v_mov_b32_e32 v16, v8
	v_mov_b32_e32 v17, v8
	v_mov_b32_e32 v24, v8
	v_mov_b32_e32 v25, v8
	v_mov_b32_e32 v32, v8
	v_mov_b32_e32 v33, v8
	v_mov_b32_e32 v44, v8
	s_mov_b64 s[14:15], 0x6000
	v_lshl_add_u64 v[40:41], v[38:39], 0, s[10:11]
	global_load_dword v60, v[40:41], off
	v_lshl_add_u64 v[40:41], v[40:41], 0, s[14:15]
	global_load_dword v61, v[40:41], off
	v_lshl_add_u64 v[40:41], v[40:41], 0, s[14:15]
	global_load_dword v62, v[40:41], off
	v_lshl_add_u64 v[40:41], v[40:41], 0, s[14:15]
	global_load_dword v63, v[40:41], off
	v_lshl_add_u64 v[40:41], v[40:41], 0, s[14:15]
	global_load_dword v64, v[40:41], off
	v_lshl_add_u64 v[40:41], v[40:41], 0, s[14:15]
	global_load_dword v65, v[40:41], off
	v_lshl_add_u64 v[40:41], v[40:41], 0, s[14:15]
	global_load_dword v66, v[40:41], off
	v_lshl_add_u64 v[40:41], v[40:41], 0, s[14:15]
	global_load_dword v67, v[40:41], off
	v_lshl_add_u64 v[40:41], v[40:41], 0, s[14:15]
	global_load_dword v68, v[40:41], off
	v_lshl_add_u64 v[40:41], v[40:41], 0, s[14:15]
	global_load_dword v69, v[40:41], off
	v_lshl_add_u64 v[40:41], v[40:41], 0, s[14:15]
	global_load_dword v70, v[40:41], off
	v_lshl_add_u64 v[40:41], v[40:41], 0, s[14:15]
	global_load_dword v71, v[40:41], off
	v_lshl_add_u64 v[40:41], v[40:41], 0, s[14:15]
	global_load_dword v72, v[40:41], off
	v_lshl_add_u64 v[40:41], v[40:41], 0, s[14:15]
	global_load_dword v73, v[40:41], off
	v_lshl_add_u64 v[40:41], v[40:41], 0, s[14:15]
	global_load_dword v74, v[40:41], off
	v_lshl_add_u64 v[40:41], v[40:41], 0, s[14:15]
	global_load_dword v75, v[40:41], off
	s_add_u32 s10, s10, 0x60000
	s_addc_u32 s11, s11, 0
.LBB0_672:
	v_lshl_add_u64 v[40:41], v[38:39], 0, s[10:11]
	global_load_dword v76, v[40:41], off
	v_lshl_add_u64 v[40:41], v[40:41], 0, s[14:15]
	global_load_dword v77, v[40:41], off
	v_lshl_add_u64 v[40:41], v[40:41], 0, s[14:15]
	global_load_dword v78, v[40:41], off
	v_lshl_add_u64 v[40:41], v[40:41], 0, s[14:15]
	global_load_dword v79, v[40:41], off
	v_lshl_add_u64 v[40:41], v[40:41], 0, s[14:15]
	global_load_dword v80, v[40:41], off
	v_lshl_add_u64 v[40:41], v[40:41], 0, s[14:15]
	global_load_dword v81, v[40:41], off
	v_lshl_add_u64 v[40:41], v[40:41], 0, s[14:15]
	global_load_dword v82, v[40:41], off
	v_lshl_add_u64 v[40:41], v[40:41], 0, s[14:15]
	global_load_dword v83, v[40:41], off
	v_lshl_add_u64 v[40:41], v[40:41], 0, s[14:15]
	global_load_dword v84, v[40:41], off
	v_lshl_add_u64 v[40:41], v[40:41], 0, s[14:15]
	global_load_dword v85, v[40:41], off
	v_lshl_add_u64 v[40:41], v[40:41], 0, s[14:15]
	global_load_dword v86, v[40:41], off
	v_lshl_add_u64 v[40:41], v[40:41], 0, s[14:15]
	global_load_dword v87, v[40:41], off
	v_lshl_add_u64 v[40:41], v[40:41], 0, s[14:15]
	global_load_dword v88, v[40:41], off
	v_lshl_add_u64 v[40:41], v[40:41], 0, s[14:15]
	global_load_dword v89, v[40:41], off
	v_lshl_add_u64 v[40:41], v[40:41], 0, s[14:15]
	global_load_dword v90, v[40:41], off
	v_lshl_add_u64 v[40:41], v[40:41], 0, s[14:15]
	global_load_dword v91, v[40:41], off
	s_add_u32 s10, s10, 0x60000
	s_addc_u32 s11, s11, 0
	ds_read_b128 v[100:103], v43 offset:0
	ds_read_b128 v[104:107], v43 offset:4096
	ds_read_b128 v[108:111], v43 offset:8192
	ds_read_b128 v[112:115], v43 offset:12288
	ds_read_b128 v[116:119], v43 offset:16384
	ds_read_b128 v[120:123], v43 offset:20480
	ds_read_b128 v[124:127], v43 offset:24576
	ds_read_b128 v[128:131], v43 offset:28672
	ds_read_b128 v[132:135], v43 offset:32768
	s_waitcnt vmcnt(28) lgkmcnt(0)
	v_fmac_f32_e32 v8, v60, v100
	v_fmac_f32_e32 v9, v60, v104
	v_fmac_f32_e32 v16, v60, v108
	v_fmac_f32_e32 v17, v60, v112
	v_fmac_f32_e32 v24, v60, v116
	v_fmac_f32_e32 v25, v60, v120
	v_fmac_f32_e32 v32, v60, v124
	v_fmac_f32_e32 v33, v60, v128
	v_fmac_f32_e32 v44, v60, v132
	v_fmac_f32_e32 v8, v61, v101
	v_fmac_f32_e32 v9, v61, v105
	v_fmac_f32_e32 v16, v61, v109
	v_fmac_f32_e32 v17, v61, v113
	v_fmac_f32_e32 v24, v61, v117
	v_fmac_f32_e32 v25, v61, v121
	v_fmac_f32_e32 v32, v61, v125
	v_fmac_f32_e32 v33, v61, v129
	v_fmac_f32_e32 v44, v61, v133
	v_fmac_f32_e32 v8, v62, v102
	v_fmac_f32_e32 v9, v62, v106
	v_fmac_f32_e32 v16, v62, v110
	v_fmac_f32_e32 v17, v62, v114
	v_fmac_f32_e32 v24, v62, v118
	v_fmac_f32_e32 v25, v62, v122
	v_fmac_f32_e32 v32, v62, v126
	v_fmac_f32_e32 v33, v62, v130
	v_fmac_f32_e32 v44, v62, v134
	v_fmac_f32_e32 v8, v63, v103
	v_fmac_f32_e32 v9, v63, v107
	v_fmac_f32_e32 v16, v63, v111
	v_fmac_f32_e32 v17, v63, v115
	v_fmac_f32_e32 v24, v63, v119
	v_fmac_f32_e32 v25, v63, v123
	v_fmac_f32_e32 v32, v63, v127
	v_fmac_f32_e32 v33, v63, v131
	v_fmac_f32_e32 v44, v63, v135
	ds_read_b128 v[100:103], v43 offset:16
	ds_read_b128 v[104:107], v43 offset:4112
	ds_read_b128 v[108:111], v43 offset:8208
	ds_read_b128 v[112:115], v43 offset:12304
	ds_read_b128 v[116:119], v43 offset:16400
	ds_read_b128 v[120:123], v43 offset:20496
	ds_read_b128 v[124:127], v43 offset:24592
	ds_read_b128 v[128:131], v43 offset:28688
	ds_read_b128 v[132:135], v43 offset:32784
	s_waitcnt vmcnt(24) lgkmcnt(0)
	v_fmac_f32_e32 v8, v64, v100
	v_fmac_f32_e32 v9, v64, v104
	v_fmac_f32_e32 v16, v64, v108
	v_fmac_f32_e32 v17, v64, v112
	v_fmac_f32_e32 v24, v64, v116
	v_fmac_f32_e32 v25, v64, v120
	v_fmac_f32_e32 v32, v64, v124
	v_fmac_f32_e32 v33, v64, v128
	v_fmac_f32_e32 v44, v64, v132
	v_fmac_f32_e32 v8, v65, v101
	v_fmac_f32_e32 v9, v65, v105
	v_fmac_f32_e32 v16, v65, v109
	v_fmac_f32_e32 v17, v65, v113
	v_fmac_f32_e32 v24, v65, v117
	v_fmac_f32_e32 v25, v65, v121
	v_fmac_f32_e32 v32, v65, v125
	v_fmac_f32_e32 v33, v65, v129
	v_fmac_f32_e32 v44, v65, v133
	v_fmac_f32_e32 v8, v66, v102
	v_fmac_f32_e32 v9, v66, v106
	v_fmac_f32_e32 v16, v66, v110
	v_fmac_f32_e32 v17, v66, v114
	v_fmac_f32_e32 v24, v66, v118
	v_fmac_f32_e32 v25, v66, v122
	v_fmac_f32_e32 v32, v66, v126
	v_fmac_f32_e32 v33, v66, v130
	v_fmac_f32_e32 v44, v66, v134
	v_fmac_f32_e32 v8, v67, v103
	v_fmac_f32_e32 v9, v67, v107
	v_fmac_f32_e32 v16, v67, v111
	v_fmac_f32_e32 v17, v67, v115
	v_fmac_f32_e32 v24, v67, v119
	v_fmac_f32_e32 v25, v67, v123
	v_fmac_f32_e32 v32, v67, v127
	v_fmac_f32_e32 v33, v67, v131
	v_fmac_f32_e32 v44, v67, v135
	ds_read_b128 v[100:103], v43 offset:32
	ds_read_b128 v[104:107], v43 offset:4128
	ds_read_b128 v[108:111], v43 offset:8224
	ds_read_b128 v[112:115], v43 offset:12320
	ds_read_b128 v[116:119], v43 offset:16416
	ds_read_b128 v[120:123], v43 offset:20512
	ds_read_b128 v[124:127], v43 offset:24608
	ds_read_b128 v[128:131], v43 offset:28704
	ds_read_b128 v[132:135], v43 offset:32800
	s_waitcnt vmcnt(20) lgkmcnt(0)
	v_fmac_f32_e32 v8, v68, v100
	v_fmac_f32_e32 v9, v68, v104
	v_fmac_f32_e32 v16, v68, v108
	v_fmac_f32_e32 v17, v68, v112
	v_fmac_f32_e32 v24, v68, v116
	v_fmac_f32_e32 v25, v68, v120
	v_fmac_f32_e32 v32, v68, v124
	v_fmac_f32_e32 v33, v68, v128
	v_fmac_f32_e32 v44, v68, v132
	v_fmac_f32_e32 v8, v69, v101
	v_fmac_f32_e32 v9, v69, v105
	v_fmac_f32_e32 v16, v69, v109
	v_fmac_f32_e32 v17, v69, v113
	v_fmac_f32_e32 v24, v69, v117
	v_fmac_f32_e32 v25, v69, v121
	v_fmac_f32_e32 v32, v69, v125
	v_fmac_f32_e32 v33, v69, v129
	v_fmac_f32_e32 v44, v69, v133
	v_fmac_f32_e32 v8, v70, v102
	v_fmac_f32_e32 v9, v70, v106
	v_fmac_f32_e32 v16, v70, v110
	v_fmac_f32_e32 v17, v70, v114
	v_fmac_f32_e32 v24, v70, v118
	v_fmac_f32_e32 v25, v70, v122
	v_fmac_f32_e32 v32, v70, v126
	v_fmac_f32_e32 v33, v70, v130
	v_fmac_f32_e32 v44, v70, v134
	v_fmac_f32_e32 v8, v71, v103
	v_fmac_f32_e32 v9, v71, v107
	v_fmac_f32_e32 v16, v71, v111
	v_fmac_f32_e32 v17, v71, v115
	v_fmac_f32_e32 v24, v71, v119
	v_fmac_f32_e32 v25, v71, v123
	v_fmac_f32_e32 v32, v71, v127
	v_fmac_f32_e32 v33, v71, v131
	v_fmac_f32_e32 v44, v71, v135
	ds_read_b128 v[100:103], v43 offset:48
	ds_read_b128 v[104:107], v43 offset:4144
	ds_read_b128 v[108:111], v43 offset:8240
	ds_read_b128 v[112:115], v43 offset:12336
	ds_read_b128 v[116:119], v43 offset:16432
	ds_read_b128 v[120:123], v43 offset:20528
	ds_read_b128 v[124:127], v43 offset:24624
	ds_read_b128 v[128:131], v43 offset:28720
	ds_read_b128 v[132:135], v43 offset:32816
	s_waitcnt vmcnt(16) lgkmcnt(0)
	v_fmac_f32_e32 v8, v72, v100
	v_fmac_f32_e32 v9, v72, v104
	v_fmac_f32_e32 v16, v72, v108
	v_fmac_f32_e32 v17, v72, v112
	v_fmac_f32_e32 v24, v72, v116
	v_fmac_f32_e32 v25, v72, v120
	v_fmac_f32_e32 v32, v72, v124
	v_fmac_f32_e32 v33, v72, v128
	v_fmac_f32_e32 v44, v72, v132
	v_fmac_f32_e32 v8, v73, v101
	v_fmac_f32_e32 v9, v73, v105
	v_fmac_f32_e32 v16, v73, v109
	v_fmac_f32_e32 v17, v73, v113
	v_fmac_f32_e32 v24, v73, v117
	v_fmac_f32_e32 v25, v73, v121
	v_fmac_f32_e32 v32, v73, v125
	v_fmac_f32_e32 v33, v73, v129
	v_fmac_f32_e32 v44, v73, v133
	v_fmac_f32_e32 v8, v74, v102
	v_fmac_f32_e32 v9, v74, v106
	v_fmac_f32_e32 v16, v74, v110
	v_fmac_f32_e32 v17, v74, v114
	v_fmac_f32_e32 v24, v74, v118
	v_fmac_f32_e32 v25, v74, v122
	v_fmac_f32_e32 v32, v74, v126
	v_fmac_f32_e32 v33, v74, v130
	v_fmac_f32_e32 v44, v74, v134
	v_fmac_f32_e32 v8, v75, v103
	v_fmac_f32_e32 v9, v75, v107
	v_fmac_f32_e32 v16, v75, v111
	v_fmac_f32_e32 v17, v75, v115
	v_fmac_f32_e32 v24, v75, v119
	v_fmac_f32_e32 v25, v75, v123
	v_fmac_f32_e32 v32, v75, v127
	v_fmac_f32_e32 v33, v75, v131
	v_fmac_f32_e32 v44, v75, v135
	v_add_u32_e32 v43, 64, v43
	v_lshl_add_u64 v[40:41], v[38:39], 0, s[10:11]
	global_load_dword v60, v[40:41], off
	v_lshl_add_u64 v[40:41], v[40:41], 0, s[14:15]
	global_load_dword v61, v[40:41], off
	v_lshl_add_u64 v[40:41], v[40:41], 0, s[14:15]
	global_load_dword v62, v[40:41], off
	v_lshl_add_u64 v[40:41], v[40:41], 0, s[14:15]
	global_load_dword v63, v[40:41], off
	v_lshl_add_u64 v[40:41], v[40:41], 0, s[14:15]
	global_load_dword v64, v[40:41], off
	v_lshl_add_u64 v[40:41], v[40:41], 0, s[14:15]
	global_load_dword v65, v[40:41], off
	v_lshl_add_u64 v[40:41], v[40:41], 0, s[14:15]
	global_load_dword v66, v[40:41], off
	v_lshl_add_u64 v[40:41], v[40:41], 0, s[14:15]
	global_load_dword v67, v[40:41], off
	v_lshl_add_u64 v[40:41], v[40:41], 0, s[14:15]
	global_load_dword v68, v[40:41], off
	v_lshl_add_u64 v[40:41], v[40:41], 0, s[14:15]
	global_load_dword v69, v[40:41], off
	v_lshl_add_u64 v[40:41], v[40:41], 0, s[14:15]
	global_load_dword v70, v[40:41], off
	v_lshl_add_u64 v[40:41], v[40:41], 0, s[14:15]
	global_load_dword v71, v[40:41], off
	v_lshl_add_u64 v[40:41], v[40:41], 0, s[14:15]
	global_load_dword v72, v[40:41], off
	v_lshl_add_u64 v[40:41], v[40:41], 0, s[14:15]
	global_load_dword v73, v[40:41], off
	v_lshl_add_u64 v[40:41], v[40:41], 0, s[14:15]
	global_load_dword v74, v[40:41], off
	v_lshl_add_u64 v[40:41], v[40:41], 0, s[14:15]
	global_load_dword v75, v[40:41], off
	s_add_u32 s10, s10, 0x60000
	s_addc_u32 s11, s11, 0
	ds_read_b128 v[100:103], v43 offset:0
	ds_read_b128 v[104:107], v43 offset:4096
	ds_read_b128 v[108:111], v43 offset:8192
	ds_read_b128 v[112:115], v43 offset:12288
	ds_read_b128 v[116:119], v43 offset:16384
	ds_read_b128 v[120:123], v43 offset:20480
	ds_read_b128 v[124:127], v43 offset:24576
	ds_read_b128 v[128:131], v43 offset:28672
	ds_read_b128 v[132:135], v43 offset:32768
	s_waitcnt vmcnt(28) lgkmcnt(0)
	v_fmac_f32_e32 v8, v76, v100
	v_fmac_f32_e32 v9, v76, v104
	v_fmac_f32_e32 v16, v76, v108
	v_fmac_f32_e32 v17, v76, v112
	v_fmac_f32_e32 v24, v76, v116
	v_fmac_f32_e32 v25, v76, v120
	v_fmac_f32_e32 v32, v76, v124
	v_fmac_f32_e32 v33, v76, v128
	v_fmac_f32_e32 v44, v76, v132
	v_fmac_f32_e32 v8, v77, v101
	v_fmac_f32_e32 v9, v77, v105
	v_fmac_f32_e32 v16, v77, v109
	v_fmac_f32_e32 v17, v77, v113
	v_fmac_f32_e32 v24, v77, v117
	v_fmac_f32_e32 v25, v77, v121
	v_fmac_f32_e32 v32, v77, v125
	v_fmac_f32_e32 v33, v77, v129
	v_fmac_f32_e32 v44, v77, v133
	v_fmac_f32_e32 v8, v78, v102
	v_fmac_f32_e32 v9, v78, v106
	v_fmac_f32_e32 v16, v78, v110
	v_fmac_f32_e32 v17, v78, v114
	v_fmac_f32_e32 v24, v78, v118
	v_fmac_f32_e32 v25, v78, v122
	v_fmac_f32_e32 v32, v78, v126
	v_fmac_f32_e32 v33, v78, v130
	v_fmac_f32_e32 v44, v78, v134
	v_fmac_f32_e32 v8, v79, v103
	v_fmac_f32_e32 v9, v79, v107
	v_fmac_f32_e32 v16, v79, v111
	v_fmac_f32_e32 v17, v79, v115
	v_fmac_f32_e32 v24, v79, v119
	v_fmac_f32_e32 v25, v79, v123
	v_fmac_f32_e32 v32, v79, v127
	v_fmac_f32_e32 v33, v79, v131
	v_fmac_f32_e32 v44, v79, v135
	ds_read_b128 v[100:103], v43 offset:16
	ds_read_b128 v[104:107], v43 offset:4112
	ds_read_b128 v[108:111], v43 offset:8208
	ds_read_b128 v[112:115], v43 offset:12304
	ds_read_b128 v[116:119], v43 offset:16400
	ds_read_b128 v[120:123], v43 offset:20496
	ds_read_b128 v[124:127], v43 offset:24592
	ds_read_b128 v[128:131], v43 offset:28688
	ds_read_b128 v[132:135], v43 offset:32784
	s_waitcnt vmcnt(24) lgkmcnt(0)
	v_fmac_f32_e32 v8, v80, v100
	v_fmac_f32_e32 v9, v80, v104
	v_fmac_f32_e32 v16, v80, v108
	v_fmac_f32_e32 v17, v80, v112
	v_fmac_f32_e32 v24, v80, v116
	v_fmac_f32_e32 v25, v80, v120
	v_fmac_f32_e32 v32, v80, v124
	v_fmac_f32_e32 v33, v80, v128
	v_fmac_f32_e32 v44, v80, v132
	v_fmac_f32_e32 v8, v81, v101
	v_fmac_f32_e32 v9, v81, v105
	v_fmac_f32_e32 v16, v81, v109
	v_fmac_f32_e32 v17, v81, v113
	v_fmac_f32_e32 v24, v81, v117
	v_fmac_f32_e32 v25, v81, v121
	v_fmac_f32_e32 v32, v81, v125
	v_fmac_f32_e32 v33, v81, v129
	v_fmac_f32_e32 v44, v81, v133
	v_fmac_f32_e32 v8, v82, v102
	v_fmac_f32_e32 v9, v82, v106
	v_fmac_f32_e32 v16, v82, v110
	v_fmac_f32_e32 v17, v82, v114
	v_fmac_f32_e32 v24, v82, v118
	v_fmac_f32_e32 v25, v82, v122
	v_fmac_f32_e32 v32, v82, v126
	v_fmac_f32_e32 v33, v82, v130
	v_fmac_f32_e32 v44, v82, v134
	v_fmac_f32_e32 v8, v83, v103
	v_fmac_f32_e32 v9, v83, v107
	v_fmac_f32_e32 v16, v83, v111
	v_fmac_f32_e32 v17, v83, v115
	v_fmac_f32_e32 v24, v83, v119
	v_fmac_f32_e32 v25, v83, v123
	v_fmac_f32_e32 v32, v83, v127
	v_fmac_f32_e32 v33, v83, v131
	v_fmac_f32_e32 v44, v83, v135
	ds_read_b128 v[100:103], v43 offset:32
	ds_read_b128 v[104:107], v43 offset:4128
	ds_read_b128 v[108:111], v43 offset:8224
	ds_read_b128 v[112:115], v43 offset:12320
	ds_read_b128 v[116:119], v43 offset:16416
	ds_read_b128 v[120:123], v43 offset:20512
	ds_read_b128 v[124:127], v43 offset:24608
	ds_read_b128 v[128:131], v43 offset:28704
	ds_read_b128 v[132:135], v43 offset:32800
	s_waitcnt vmcnt(20) lgkmcnt(0)
	v_fmac_f32_e32 v8, v84, v100
	v_fmac_f32_e32 v9, v84, v104
	v_fmac_f32_e32 v16, v84, v108
	v_fmac_f32_e32 v17, v84, v112
	v_fmac_f32_e32 v24, v84, v116
	v_fmac_f32_e32 v25, v84, v120
	v_fmac_f32_e32 v32, v84, v124
	v_fmac_f32_e32 v33, v84, v128
	v_fmac_f32_e32 v44, v84, v132
	v_fmac_f32_e32 v8, v85, v101
	v_fmac_f32_e32 v9, v85, v105
	v_fmac_f32_e32 v16, v85, v109
	v_fmac_f32_e32 v17, v85, v113
	v_fmac_f32_e32 v24, v85, v117
	v_fmac_f32_e32 v25, v85, v121
	v_fmac_f32_e32 v32, v85, v125
	v_fmac_f32_e32 v33, v85, v129
	v_fmac_f32_e32 v44, v85, v133
	v_fmac_f32_e32 v8, v86, v102
	v_fmac_f32_e32 v9, v86, v106
	v_fmac_f32_e32 v16, v86, v110
	v_fmac_f32_e32 v17, v86, v114
	v_fmac_f32_e32 v24, v86, v118
	v_fmac_f32_e32 v25, v86, v122
	v_fmac_f32_e32 v32, v86, v126
	v_fmac_f32_e32 v33, v86, v130
	v_fmac_f32_e32 v44, v86, v134
	v_fmac_f32_e32 v8, v87, v103
	v_fmac_f32_e32 v9, v87, v107
	v_fmac_f32_e32 v16, v87, v111
	v_fmac_f32_e32 v17, v87, v115
	v_fmac_f32_e32 v24, v87, v119
	v_fmac_f32_e32 v25, v87, v123
	v_fmac_f32_e32 v32, v87, v127
	v_fmac_f32_e32 v33, v87, v131
	v_fmac_f32_e32 v44, v87, v135
	ds_read_b128 v[100:103], v43 offset:48
	ds_read_b128 v[104:107], v43 offset:4144
	ds_read_b128 v[108:111], v43 offset:8240
	ds_read_b128 v[112:115], v43 offset:12336
	ds_read_b128 v[116:119], v43 offset:16432
	ds_read_b128 v[120:123], v43 offset:20528
	ds_read_b128 v[124:127], v43 offset:24624
	ds_read_b128 v[128:131], v43 offset:28720
	ds_read_b128 v[132:135], v43 offset:32816
	s_waitcnt vmcnt(16) lgkmcnt(0)
	v_fmac_f32_e32 v8, v88, v100
	v_fmac_f32_e32 v9, v88, v104
	v_fmac_f32_e32 v16, v88, v108
	v_fmac_f32_e32 v17, v88, v112
	v_fmac_f32_e32 v24, v88, v116
	v_fmac_f32_e32 v25, v88, v120
	v_fmac_f32_e32 v32, v88, v124
	v_fmac_f32_e32 v33, v88, v128
	v_fmac_f32_e32 v44, v88, v132
	v_fmac_f32_e32 v8, v89, v101
	v_fmac_f32_e32 v9, v89, v105
	v_fmac_f32_e32 v16, v89, v109
	v_fmac_f32_e32 v17, v89, v113
	v_fmac_f32_e32 v24, v89, v117
	v_fmac_f32_e32 v25, v89, v121
	v_fmac_f32_e32 v32, v89, v125
	v_fmac_f32_e32 v33, v89, v129
	v_fmac_f32_e32 v44, v89, v133
	v_fmac_f32_e32 v8, v90, v102
	v_fmac_f32_e32 v9, v90, v106
	v_fmac_f32_e32 v16, v90, v110
	v_fmac_f32_e32 v17, v90, v114
	v_fmac_f32_e32 v24, v90, v118
	v_fmac_f32_e32 v25, v90, v122
	v_fmac_f32_e32 v32, v90, v126
	v_fmac_f32_e32 v33, v90, v130
	v_fmac_f32_e32 v44, v90, v134
	v_fmac_f32_e32 v8, v91, v103
	v_fmac_f32_e32 v9, v91, v107
	v_fmac_f32_e32 v16, v91, v111
	v_fmac_f32_e32 v17, v91, v115
	v_fmac_f32_e32 v24, v91, v119
	v_fmac_f32_e32 v25, v91, v123
	v_fmac_f32_e32 v32, v91, v127
	v_fmac_f32_e32 v33, v91, v131
	v_fmac_f32_e32 v44, v91, v135
	v_add_u32_e32 v43, 64, v43
	s_cmp_eq_u32 s10, 0x5a0000
	s_cbranch_scc0 .LBB0_672
	v_lshl_add_u64 v[40:41], v[38:39], 0, s[10:11]
	global_load_dword v76, v[40:41], off
	v_lshl_add_u64 v[40:41], v[40:41], 0, s[14:15]
	global_load_dword v77, v[40:41], off
	v_lshl_add_u64 v[40:41], v[40:41], 0, s[14:15]
	global_load_dword v78, v[40:41], off
	v_lshl_add_u64 v[40:41], v[40:41], 0, s[14:15]
	global_load_dword v79, v[40:41], off
	v_lshl_add_u64 v[40:41], v[40:41], 0, s[14:15]
	global_load_dword v80, v[40:41], off
	v_lshl_add_u64 v[40:41], v[40:41], 0, s[14:15]
	global_load_dword v81, v[40:41], off
	v_lshl_add_u64 v[40:41], v[40:41], 0, s[14:15]
	global_load_dword v82, v[40:41], off
	v_lshl_add_u64 v[40:41], v[40:41], 0, s[14:15]
	global_load_dword v83, v[40:41], off
	v_lshl_add_u64 v[40:41], v[40:41], 0, s[14:15]
	global_load_dword v84, v[40:41], off
	v_lshl_add_u64 v[40:41], v[40:41], 0, s[14:15]
	global_load_dword v85, v[40:41], off
	v_lshl_add_u64 v[40:41], v[40:41], 0, s[14:15]
	global_load_dword v86, v[40:41], off
	v_lshl_add_u64 v[40:41], v[40:41], 0, s[14:15]
	global_load_dword v87, v[40:41], off
	v_lshl_add_u64 v[40:41], v[40:41], 0, s[14:15]
	global_load_dword v88, v[40:41], off
	v_lshl_add_u64 v[40:41], v[40:41], 0, s[14:15]
	global_load_dword v89, v[40:41], off
	v_lshl_add_u64 v[40:41], v[40:41], 0, s[14:15]
	global_load_dword v90, v[40:41], off
	v_lshl_add_u64 v[40:41], v[40:41], 0, s[14:15]
	global_load_dword v91, v[40:41], off
	s_add_u32 s10, s10, 0x60000
	s_addc_u32 s11, s11, 0
	ds_read_b128 v[100:103], v43 offset:0
	ds_read_b128 v[104:107], v43 offset:4096
	ds_read_b128 v[108:111], v43 offset:8192
	ds_read_b128 v[112:115], v43 offset:12288
	ds_read_b128 v[116:119], v43 offset:16384
	ds_read_b128 v[120:123], v43 offset:20480
	ds_read_b128 v[124:127], v43 offset:24576
	ds_read_b128 v[128:131], v43 offset:28672
	ds_read_b128 v[132:135], v43 offset:32768
	s_waitcnt vmcnt(28) lgkmcnt(0)
	v_fmac_f32_e32 v8, v60, v100
	v_fmac_f32_e32 v9, v60, v104
	v_fmac_f32_e32 v16, v60, v108
	v_fmac_f32_e32 v17, v60, v112
	v_fmac_f32_e32 v24, v60, v116
	v_fmac_f32_e32 v25, v60, v120
	v_fmac_f32_e32 v32, v60, v124
	v_fmac_f32_e32 v33, v60, v128
	v_fmac_f32_e32 v44, v60, v132
	v_fmac_f32_e32 v8, v61, v101
	v_fmac_f32_e32 v9, v61, v105
	v_fmac_f32_e32 v16, v61, v109
	v_fmac_f32_e32 v17, v61, v113
	v_fmac_f32_e32 v24, v61, v117
	v_fmac_f32_e32 v25, v61, v121
	v_fmac_f32_e32 v32, v61, v125
	v_fmac_f32_e32 v33, v61, v129
	v_fmac_f32_e32 v44, v61, v133
	v_fmac_f32_e32 v8, v62, v102
	v_fmac_f32_e32 v9, v62, v106
	v_fmac_f32_e32 v16, v62, v110
	v_fmac_f32_e32 v17, v62, v114
	v_fmac_f32_e32 v24, v62, v118
	v_fmac_f32_e32 v25, v62, v122
	v_fmac_f32_e32 v32, v62, v126
	v_fmac_f32_e32 v33, v62, v130
	v_fmac_f32_e32 v44, v62, v134
	v_fmac_f32_e32 v8, v63, v103
	v_fmac_f32_e32 v9, v63, v107
	v_fmac_f32_e32 v16, v63, v111
	v_fmac_f32_e32 v17, v63, v115
	v_fmac_f32_e32 v24, v63, v119
	v_fmac_f32_e32 v25, v63, v123
	v_fmac_f32_e32 v32, v63, v127
	v_fmac_f32_e32 v33, v63, v131
	v_fmac_f32_e32 v44, v63, v135
	ds_read_b128 v[100:103], v43 offset:16
	ds_read_b128 v[104:107], v43 offset:4112
	ds_read_b128 v[108:111], v43 offset:8208
	ds_read_b128 v[112:115], v43 offset:12304
	ds_read_b128 v[116:119], v43 offset:16400
	ds_read_b128 v[120:123], v43 offset:20496
	ds_read_b128 v[124:127], v43 offset:24592
	ds_read_b128 v[128:131], v43 offset:28688
	ds_read_b128 v[132:135], v43 offset:32784
	s_waitcnt vmcnt(24) lgkmcnt(0)
	v_fmac_f32_e32 v8, v64, v100
	v_fmac_f32_e32 v9, v64, v104
	v_fmac_f32_e32 v16, v64, v108
	v_fmac_f32_e32 v17, v64, v112
	v_fmac_f32_e32 v24, v64, v116
	v_fmac_f32_e32 v25, v64, v120
	v_fmac_f32_e32 v32, v64, v124
	v_fmac_f32_e32 v33, v64, v128
	v_fmac_f32_e32 v44, v64, v132
	v_fmac_f32_e32 v8, v65, v101
	v_fmac_f32_e32 v9, v65, v105
	v_fmac_f32_e32 v16, v65, v109
	v_fmac_f32_e32 v17, v65, v113
	v_fmac_f32_e32 v24, v65, v117
	v_fmac_f32_e32 v25, v65, v121
	v_fmac_f32_e32 v32, v65, v125
	v_fmac_f32_e32 v33, v65, v129
	v_fmac_f32_e32 v44, v65, v133
	v_fmac_f32_e32 v8, v66, v102
	v_fmac_f32_e32 v9, v66, v106
	v_fmac_f32_e32 v16, v66, v110
	v_fmac_f32_e32 v17, v66, v114
	v_fmac_f32_e32 v24, v66, v118
	v_fmac_f32_e32 v25, v66, v122
	v_fmac_f32_e32 v32, v66, v126
	v_fmac_f32_e32 v33, v66, v130
	v_fmac_f32_e32 v44, v66, v134
	v_fmac_f32_e32 v8, v67, v103
	v_fmac_f32_e32 v9, v67, v107
	v_fmac_f32_e32 v16, v67, v111
	v_fmac_f32_e32 v17, v67, v115
	v_fmac_f32_e32 v24, v67, v119
	v_fmac_f32_e32 v25, v67, v123
	v_fmac_f32_e32 v32, v67, v127
	v_fmac_f32_e32 v33, v67, v131
	v_fmac_f32_e32 v44, v67, v135
	ds_read_b128 v[100:103], v43 offset:32
	ds_read_b128 v[104:107], v43 offset:4128
	ds_read_b128 v[108:111], v43 offset:8224
	ds_read_b128 v[112:115], v43 offset:12320
	ds_read_b128 v[116:119], v43 offset:16416
	ds_read_b128 v[120:123], v43 offset:20512
	ds_read_b128 v[124:127], v43 offset:24608
	ds_read_b128 v[128:131], v43 offset:28704
	ds_read_b128 v[132:135], v43 offset:32800
	s_waitcnt vmcnt(20) lgkmcnt(0)
	v_fmac_f32_e32 v8, v68, v100
	v_fmac_f32_e32 v9, v68, v104
	v_fmac_f32_e32 v16, v68, v108
	v_fmac_f32_e32 v17, v68, v112
	v_fmac_f32_e32 v24, v68, v116
	v_fmac_f32_e32 v25, v68, v120
	v_fmac_f32_e32 v32, v68, v124
	v_fmac_f32_e32 v33, v68, v128
	v_fmac_f32_e32 v44, v68, v132
	v_fmac_f32_e32 v8, v69, v101
	v_fmac_f32_e32 v9, v69, v105
	v_fmac_f32_e32 v16, v69, v109
	v_fmac_f32_e32 v17, v69, v113
	v_fmac_f32_e32 v24, v69, v117
	v_fmac_f32_e32 v25, v69, v121
	v_fmac_f32_e32 v32, v69, v125
	v_fmac_f32_e32 v33, v69, v129
	v_fmac_f32_e32 v44, v69, v133
	v_fmac_f32_e32 v8, v70, v102
	v_fmac_f32_e32 v9, v70, v106
	v_fmac_f32_e32 v16, v70, v110
	v_fmac_f32_e32 v17, v70, v114
	v_fmac_f32_e32 v24, v70, v118
	v_fmac_f32_e32 v25, v70, v122
	v_fmac_f32_e32 v32, v70, v126
	v_fmac_f32_e32 v33, v70, v130
	v_fmac_f32_e32 v44, v70, v134
	v_fmac_f32_e32 v8, v71, v103
	v_fmac_f32_e32 v9, v71, v107
	v_fmac_f32_e32 v16, v71, v111
	v_fmac_f32_e32 v17, v71, v115
	v_fmac_f32_e32 v24, v71, v119
	v_fmac_f32_e32 v25, v71, v123
	v_fmac_f32_e32 v32, v71, v127
	v_fmac_f32_e32 v33, v71, v131
	v_fmac_f32_e32 v44, v71, v135
	ds_read_b128 v[100:103], v43 offset:48
	ds_read_b128 v[104:107], v43 offset:4144
	ds_read_b128 v[108:111], v43 offset:8240
	ds_read_b128 v[112:115], v43 offset:12336
	ds_read_b128 v[116:119], v43 offset:16432
	ds_read_b128 v[120:123], v43 offset:20528
	ds_read_b128 v[124:127], v43 offset:24624
	ds_read_b128 v[128:131], v43 offset:28720
	ds_read_b128 v[132:135], v43 offset:32816
	s_waitcnt vmcnt(16) lgkmcnt(0)
	v_fmac_f32_e32 v8, v72, v100
	v_fmac_f32_e32 v9, v72, v104
	v_fmac_f32_e32 v16, v72, v108
	v_fmac_f32_e32 v17, v72, v112
	v_fmac_f32_e32 v24, v72, v116
	v_fmac_f32_e32 v25, v72, v120
	v_fmac_f32_e32 v32, v72, v124
	v_fmac_f32_e32 v33, v72, v128
	v_fmac_f32_e32 v44, v72, v132
	v_fmac_f32_e32 v8, v73, v101
	v_fmac_f32_e32 v9, v73, v105
	v_fmac_f32_e32 v16, v73, v109
	v_fmac_f32_e32 v17, v73, v113
	v_fmac_f32_e32 v24, v73, v117
	v_fmac_f32_e32 v25, v73, v121
	v_fmac_f32_e32 v32, v73, v125
	v_fmac_f32_e32 v33, v73, v129
	v_fmac_f32_e32 v44, v73, v133
	v_fmac_f32_e32 v8, v74, v102
	v_fmac_f32_e32 v9, v74, v106
	v_fmac_f32_e32 v16, v74, v110
	v_fmac_f32_e32 v17, v74, v114
	v_fmac_f32_e32 v24, v74, v118
	v_fmac_f32_e32 v25, v74, v122
	v_fmac_f32_e32 v32, v74, v126
	v_fmac_f32_e32 v33, v74, v130
	v_fmac_f32_e32 v44, v74, v134
	v_fmac_f32_e32 v8, v75, v103
	v_fmac_f32_e32 v9, v75, v107
	v_fmac_f32_e32 v16, v75, v111
	v_fmac_f32_e32 v17, v75, v115
	v_fmac_f32_e32 v24, v75, v119
	v_fmac_f32_e32 v25, v75, v123
	v_fmac_f32_e32 v32, v75, v127
	v_fmac_f32_e32 v33, v75, v131
	v_fmac_f32_e32 v44, v75, v135
	v_add_u32_e32 v43, 64, v43
	ds_read_b128 v[100:103], v43 offset:0
	ds_read_b128 v[104:107], v43 offset:4096
	ds_read_b128 v[108:111], v43 offset:8192
	ds_read_b128 v[112:115], v43 offset:12288
	ds_read_b128 v[116:119], v43 offset:16384
	ds_read_b128 v[120:123], v43 offset:20480
	ds_read_b128 v[124:127], v43 offset:24576
	ds_read_b128 v[128:131], v43 offset:28672
	ds_read_b128 v[132:135], v43 offset:32768
	s_waitcnt vmcnt(12) lgkmcnt(0)
	v_fmac_f32_e32 v8, v76, v100
	v_fmac_f32_e32 v9, v76, v104
	v_fmac_f32_e32 v16, v76, v108
	v_fmac_f32_e32 v17, v76, v112
	v_fmac_f32_e32 v24, v76, v116
	v_fmac_f32_e32 v25, v76, v120
	v_fmac_f32_e32 v32, v76, v124
	v_fmac_f32_e32 v33, v76, v128
	v_fmac_f32_e32 v44, v76, v132
	v_fmac_f32_e32 v8, v77, v101
	v_fmac_f32_e32 v9, v77, v105
	v_fmac_f32_e32 v16, v77, v109
	v_fmac_f32_e32 v17, v77, v113
	v_fmac_f32_e32 v24, v77, v117
	v_fmac_f32_e32 v25, v77, v121
	v_fmac_f32_e32 v32, v77, v125
	v_fmac_f32_e32 v33, v77, v129
	v_fmac_f32_e32 v44, v77, v133
	v_fmac_f32_e32 v8, v78, v102
	v_fmac_f32_e32 v9, v78, v106
	v_fmac_f32_e32 v16, v78, v110
	v_fmac_f32_e32 v17, v78, v114
	v_fmac_f32_e32 v24, v78, v118
	v_fmac_f32_e32 v25, v78, v122
	v_fmac_f32_e32 v32, v78, v126
	v_fmac_f32_e32 v33, v78, v130
	v_fmac_f32_e32 v44, v78, v134
	v_fmac_f32_e32 v8, v79, v103
	v_fmac_f32_e32 v9, v79, v107
	v_fmac_f32_e32 v16, v79, v111
	v_fmac_f32_e32 v17, v79, v115
	v_fmac_f32_e32 v24, v79, v119
	v_fmac_f32_e32 v25, v79, v123
	v_fmac_f32_e32 v32, v79, v127
	v_fmac_f32_e32 v33, v79, v131
	v_fmac_f32_e32 v44, v79, v135
	ds_read_b128 v[100:103], v43 offset:16
	ds_read_b128 v[104:107], v43 offset:4112
	ds_read_b128 v[108:111], v43 offset:8208
	ds_read_b128 v[112:115], v43 offset:12304
	ds_read_b128 v[116:119], v43 offset:16400
	ds_read_b128 v[120:123], v43 offset:20496
	ds_read_b128 v[124:127], v43 offset:24592
	ds_read_b128 v[128:131], v43 offset:28688
	ds_read_b128 v[132:135], v43 offset:32784
	s_waitcnt vmcnt(8) lgkmcnt(0)
	v_fmac_f32_e32 v8, v80, v100
	v_fmac_f32_e32 v9, v80, v104
	v_fmac_f32_e32 v16, v80, v108
	v_fmac_f32_e32 v17, v80, v112
	v_fmac_f32_e32 v24, v80, v116
	v_fmac_f32_e32 v25, v80, v120
	v_fmac_f32_e32 v32, v80, v124
	v_fmac_f32_e32 v33, v80, v128
	v_fmac_f32_e32 v44, v80, v132
	v_fmac_f32_e32 v8, v81, v101
	v_fmac_f32_e32 v9, v81, v105
	v_fmac_f32_e32 v16, v81, v109
	v_fmac_f32_e32 v17, v81, v113
	v_fmac_f32_e32 v24, v81, v117
	v_fmac_f32_e32 v25, v81, v121
	v_fmac_f32_e32 v32, v81, v125
	v_fmac_f32_e32 v33, v81, v129
	v_fmac_f32_e32 v44, v81, v133
	v_fmac_f32_e32 v8, v82, v102
	v_fmac_f32_e32 v9, v82, v106
	v_fmac_f32_e32 v16, v82, v110
	v_fmac_f32_e32 v17, v82, v114
	v_fmac_f32_e32 v24, v82, v118
	v_fmac_f32_e32 v25, v82, v122
	v_fmac_f32_e32 v32, v82, v126
	v_fmac_f32_e32 v33, v82, v130
	v_fmac_f32_e32 v44, v82, v134
	v_fmac_f32_e32 v8, v83, v103
	v_fmac_f32_e32 v9, v83, v107
	v_fmac_f32_e32 v16, v83, v111
	v_fmac_f32_e32 v17, v83, v115
	v_fmac_f32_e32 v24, v83, v119
	v_fmac_f32_e32 v25, v83, v123
	v_fmac_f32_e32 v32, v83, v127
	v_fmac_f32_e32 v33, v83, v131
	v_fmac_f32_e32 v44, v83, v135
	ds_read_b128 v[100:103], v43 offset:32
	ds_read_b128 v[104:107], v43 offset:4128
	ds_read_b128 v[108:111], v43 offset:8224
	ds_read_b128 v[112:115], v43 offset:12320
	ds_read_b128 v[116:119], v43 offset:16416
	ds_read_b128 v[120:123], v43 offset:20512
	ds_read_b128 v[124:127], v43 offset:24608
	ds_read_b128 v[128:131], v43 offset:28704
	ds_read_b128 v[132:135], v43 offset:32800
	s_waitcnt vmcnt(4) lgkmcnt(0)
	v_fmac_f32_e32 v8, v84, v100
	v_fmac_f32_e32 v9, v84, v104
	v_fmac_f32_e32 v16, v84, v108
	v_fmac_f32_e32 v17, v84, v112
	v_fmac_f32_e32 v24, v84, v116
	v_fmac_f32_e32 v25, v84, v120
	v_fmac_f32_e32 v32, v84, v124
	v_fmac_f32_e32 v33, v84, v128
	v_fmac_f32_e32 v44, v84, v132
	v_fmac_f32_e32 v8, v85, v101
	v_fmac_f32_e32 v9, v85, v105
	v_fmac_f32_e32 v16, v85, v109
	v_fmac_f32_e32 v17, v85, v113
	v_fmac_f32_e32 v24, v85, v117
	v_fmac_f32_e32 v25, v85, v121
	v_fmac_f32_e32 v32, v85, v125
	v_fmac_f32_e32 v33, v85, v129
	v_fmac_f32_e32 v44, v85, v133
	v_fmac_f32_e32 v8, v86, v102
	v_fmac_f32_e32 v9, v86, v106
	v_fmac_f32_e32 v16, v86, v110
	v_fmac_f32_e32 v17, v86, v114
	v_fmac_f32_e32 v24, v86, v118
	v_fmac_f32_e32 v25, v86, v122
	v_fmac_f32_e32 v32, v86, v126
	v_fmac_f32_e32 v33, v86, v130
	v_fmac_f32_e32 v44, v86, v134
	v_fmac_f32_e32 v8, v87, v103
	v_fmac_f32_e32 v9, v87, v107
	v_fmac_f32_e32 v16, v87, v111
	v_fmac_f32_e32 v17, v87, v115
	v_fmac_f32_e32 v24, v87, v119
	v_fmac_f32_e32 v25, v87, v123
	v_fmac_f32_e32 v32, v87, v127
	v_fmac_f32_e32 v33, v87, v131
	v_fmac_f32_e32 v44, v87, v135
	ds_read_b128 v[100:103], v43 offset:48
	ds_read_b128 v[104:107], v43 offset:4144
	ds_read_b128 v[108:111], v43 offset:8240
	ds_read_b128 v[112:115], v43 offset:12336
	ds_read_b128 v[116:119], v43 offset:16432
	ds_read_b128 v[120:123], v43 offset:20528
	ds_read_b128 v[124:127], v43 offset:24624
	ds_read_b128 v[128:131], v43 offset:28720
	ds_read_b128 v[132:135], v43 offset:32816
	s_waitcnt vmcnt(0) lgkmcnt(0)
	v_fmac_f32_e32 v8, v88, v100
	v_fmac_f32_e32 v9, v88, v104
	v_fmac_f32_e32 v16, v88, v108
	v_fmac_f32_e32 v17, v88, v112
	v_fmac_f32_e32 v24, v88, v116
	v_fmac_f32_e32 v25, v88, v120
	v_fmac_f32_e32 v32, v88, v124
	v_fmac_f32_e32 v33, v88, v128
	v_fmac_f32_e32 v44, v88, v132
	v_fmac_f32_e32 v8, v89, v101
	v_fmac_f32_e32 v9, v89, v105
	v_fmac_f32_e32 v16, v89, v109
	v_fmac_f32_e32 v17, v89, v113
	v_fmac_f32_e32 v24, v89, v117
	v_fmac_f32_e32 v25, v89, v121
	v_fmac_f32_e32 v32, v89, v125
	v_fmac_f32_e32 v33, v89, v129
	v_fmac_f32_e32 v44, v89, v133
	v_fmac_f32_e32 v8, v90, v102
	v_fmac_f32_e32 v9, v90, v106
	v_fmac_f32_e32 v16, v90, v110
	v_fmac_f32_e32 v17, v90, v114
	v_fmac_f32_e32 v24, v90, v118
	v_fmac_f32_e32 v25, v90, v122
	v_fmac_f32_e32 v32, v90, v126
	v_fmac_f32_e32 v33, v90, v130
	v_fmac_f32_e32 v44, v90, v134
	v_fmac_f32_e32 v8, v91, v103
	v_fmac_f32_e32 v9, v91, v107
	v_fmac_f32_e32 v16, v91, v111
	v_fmac_f32_e32 v17, v91, v115
	v_fmac_f32_e32 v24, v91, v119
	v_fmac_f32_e32 v25, v91, v123
	v_fmac_f32_e32 v32, v91, v127
	v_fmac_f32_e32 v33, v91, v131
	v_fmac_f32_e32 v44, v91, v135
	v_add_u32_e32 v43, 64, v43
	s_movk_i32 s7, 0x900
	v_lshlrev_b32_e32 v148, 2, v36
	v_mul_lo_u32 v0, v42, s7
	s_movk_i32 s7, 0x240
	v_or_b32_e32 v0, v148, v0
	v_cmp_gt_i32_e32 vcc, s7, v37
	ds_write2st64_b32 v0, v8, v9 offset0:144 offset1:145
	ds_write2st64_b32 v0, v16, v17 offset0:146 offset1:147
	ds_write2st64_b32 v0, v24, v25 offset0:148 offset1:149
	ds_write2st64_b32 v0, v32, v33 offset0:150 offset1:151
	ds_write_b32 v0, v44 offset:38912
	s_waitcnt lgkmcnt(0)
	s_barrier
	s_and_saveexec_b64 s[10:11], vcc
	s_cbranch_execz .LBB0_663
	s_load_dwordx2 s[14:15], s[4:5], 0x120
	s_lshl_b64 s[16:17], s[8:9], 2
	s_load_dwordx2 s[4:5], s[4:5], 0x40
	s_mul_i32 s7, s6, 0x1800
	v_mov_b32_e32 v4, 0x9000
	s_waitcnt lgkmcnt(0)
	s_add_u32 s14, s14, s16
	s_addc_u32 s15, s15, s17
	s_add_i32 s7, s7, s8
	v_or_b32_e32 v0, s7, v36
	v_ashrrev_i32_e32 v1, 31, v0
	s_mul_i32 s6, s6, 9
	v_lshl_add_u64 v[0:1], v[0:1], 2, s[4:5]
	v_lshl_add_u64 v[2:3], s[14:15], 0, v[148:149]
	v_lshl_add_u32 v4, v37, 2, v4
	s_mov_b64 s[4:5], 0
